# v33 + sample chunk loop: compiler i1 materialisation (v_cndmask + v_cmp) of the copy flag replaced by one s_andn2_b64 (section 7.12 branch-test shortening)
# speedup vs baseline: 1.0312x; 1.0312x over previous
.LBB0_1284:
	s_waitcnt vmcnt(15)
	v_cvt_pk_bf16_f32 v40, v112, v113
	v_cvt_pk_bf16_f32 v41, v114, v115
	s_waitcnt vmcnt(13)
	v_cvt_pk_bf16_f32 v44, v104, v105
	v_cvt_pk_bf16_f32 v45, v106, v107
	v_cvt_pk_bf16_f32 v42, v116, v117
	v_cvt_pk_bf16_f32 v43, v118, v119
	ds_write2_b64 v174, v[40:41], v[44:45] offset1:72
	s_waitcnt vmcnt(12)
	v_cvt_pk_bf16_f32 v40, v108, v109
	v_cvt_pk_bf16_f32 v41, v110, v111
	v_add_u32_e32 v204, 0x1000, v174
	ds_write2_b64 v204, v[42:43], v[40:41] offset0:64 offset1:136
	s_waitcnt vmcnt(11)
	v_cvt_pk_bf16_f32 v40, v96, v97
	v_cvt_pk_bf16_f32 v41, v98, v99
	s_waitcnt vmcnt(9)
	v_cvt_pk_bf16_f32 v44, v88, v89
	v_cvt_pk_bf16_f32 v45, v90, v91
	v_cvt_pk_bf16_f32 v42, v100, v101
	v_cvt_pk_bf16_f32 v43, v102, v103
	ds_write2_b64 v174, v[40:41], v[44:45] offset0:144 offset1:216
	s_waitcnt vmcnt(8)
	v_cvt_pk_bf16_f32 v40, v92, v93
	v_cvt_pk_bf16_f32 v41, v94, v95
	v_add_u32_e32 v205, 0x1400, v174
	ds_write2_b64 v205, v[42:43], v[40:41] offset0:80 offset1:152
	s_waitcnt vmcnt(7)
	v_cvt_pk_bf16_f32 v40, v80, v81
	v_cvt_pk_bf16_f32 v41, v82, v83
	s_waitcnt vmcnt(5)
	v_cvt_pk_bf16_f32 v44, v64, v65
	v_cvt_pk_bf16_f32 v45, v66, v67
	v_add_u32_e32 v203, 0x800, v174
	v_cvt_pk_bf16_f32 v42, v84, v85
	v_cvt_pk_bf16_f32 v43, v86, v87
	ds_write2_b64 v203, v[40:41], v[44:45] offset0:32 offset1:104
	s_waitcnt vmcnt(4)
	v_cvt_pk_bf16_f32 v40, v68, v69
	v_cvt_pk_bf16_f32 v41, v70, v71
	v_add_u32_e32 v206, 0x1800, v174
	ds_write2_b64 v206, v[42:43], v[40:41] offset0:96 offset1:168
	s_waitcnt vmcnt(3)
	v_cvt_pk_bf16_f32 v40, v72, v73
	v_cvt_pk_bf16_f32 v41, v74, v75
	s_waitcnt vmcnt(1)
	v_cvt_pk_bf16_f32 v44, v32, v33
	v_cvt_pk_bf16_f32 v45, v34, v35
	ds_write2_b64 v203, v[40:41], v[44:45] offset0:176 offset1:248
	v_cvt_pk_bf16_f32 v42, v76, v77
	v_cvt_pk_bf16_f32 v43, v78, v79
	s_waitcnt vmcnt(0)
	v_cvt_pk_bf16_f32 v40, v36, v37
	v_cvt_pk_bf16_f32 v41, v38, v39
	v_add_u32_e32 v207, 0x1c00, v174
	s_andn2_b64 s[12:13], exec, s[10:11]
	s_andn2_b64 vcc, exec, s[10:11]
	ds_write2_b64 v207, v[42:43], v[40:41] offset0:112 offset1:184
	s_cbranch_vccnz .LBB0_1326
	v_add_u32_e32 v41, v199, v201
	v_subrev_u32_e32 v40, 60, v182
	v_add_u32_e32 v42, -8, v41
	v_cmp_ge_i32_e32 vcc, s53, v40
	v_cmp_gt_u32_e64 s[16:17], s92, v42
	s_and_b64 s[16:17], vcc, s[16:17]
	s_and_saveexec_b64 s[82:83], s[16:17]
	s_andn2_b64 vcc, exec, s[8:9]
	s_mov_b64 s[16:17], s[80:81]
	s_cbranch_vccnz .LBB0_1288
	v_cmp_lt_u32_e32 vcc, s93, v41
	v_and_b32_e32 v41, 8, v41
	v_cmp_ne_u32_e64 s[16:17], 0, v41
	s_and_b64 s[16:17], vcc, s[16:17]
	s_andn2_b64 vcc, s[80:81], exec
	s_and_b64 s[16:17], s[16:17], exec
	s_or_b64 s[16:17], vcc, s[16:17]
